# v4_nonorm
# speedup vs baseline: 1.0055x; 1.0055x over previous
.LBB0_1141:
	s_waitcnt vmcnt(0)
	v_mul_f32_e32 v64, v61, v61
	v_mul_f32_e32 v65, v57, v57
	v_fmac_f32_e32 v64, v60, v60
	v_fmac_f32_e32 v65, v56, v56
	v_fmac_f32_e32 v64, v62, v62
	v_fmac_f32_e32 v65, v58, v58
	v_fmac_f32_e32 v64, v63, v63
	v_fmac_f32_e32 v65, v59, v59
	v_add_f32_e32 v64, v64, v65
	v_mul_f32_e32 v65, v49, v49
	v_fmac_f32_e32 v65, v48, v48
	v_fmac_f32_e32 v65, v50, v50
	v_fmac_f32_e32 v65, v51, v51
	v_add_f32_e32 v64, v65, v64
	v_mul_f32_e32 v65, v53, v53
	v_pk_mul_f32 v[98:99], v[44:45], v[44:45]
	v_pk_mul_f32 v[100:101], v[40:41], v[40:41]
	v_fmac_f32_e32 v65, v52, v52
	v_pk_mul_f32 v[94:95], v[46:47], v[46:47]
	v_pk_mul_f32 v[96:97], v[42:43], v[42:43]
	v_mov_b32_e32 v102, v98
	v_mov_b32_e32 v103, v100
	v_mov_b32_e32 v100, v99
	v_fmac_f32_e32 v65, v54, v54
	v_pk_add_f32 v[98:99], v[102:103], v[100:101]
	v_mov_b32_e32 v100, v94
	v_mov_b32_e32 v101, v96
	v_fmac_f32_e32 v65, v55, v55
	v_pk_add_f32 v[98:99], v[100:101], v[98:99]
	v_mov_b32_e32 v96, v95
	v_add_f32_e32 v79, v65, v64
	v_pk_add_f32 v[94:95], v[96:97], v[98:99]
	v_pk_mul_f32 v[86:87], v[8:9], v[8:9]
	v_pk_mul_f32 v[92:93], v[4:5], v[4:5]
	v_add_f32_e32 v79, v95, v79
	v_pk_mul_f32 v[64:65], v[10:11], v[10:11]
	v_pk_mul_f32 v[66:67], v[6:7], v[6:7]
	v_add_f32_e32 v79, v94, v79
	v_mov_b32_e32 v94, v86
	v_mov_b32_e32 v95, v92
	v_mov_b32_e32 v92, v87
	v_pk_add_f32 v[86:87], v[94:95], v[92:93]
	v_mov_b32_e32 v92, v64
	v_mov_b32_e32 v93, v66
	v_pk_add_f32 v[86:87], v[92:93], v[86:87]
	v_mov_b32_e32 v66, v65
	v_pk_add_f32 v[64:65], v[66:67], v[86:87]
	s_add_i32 s5, s6, 0xfffff000
	v_add_f32_e32 v65, v65, v79
	v_add_f32_e32 v64, v64, v65
	ds_bpermute_b32 v65, v69, v64
	s_ashr_i32 s5, s5, 11
	s_add_i32 s5, s5, 1
	s_cmpk_gt_i32 s6, 0xfff
	s_cselect_b32 s5, s5, 0
	s_waitcnt lgkmcnt(0)
	v_add_f32_e32 v64, v64, v65
	ds_bpermute_b32 v65, v85, v64
	s_mul_hi_i32 s7, s5, 0xc000
	s_mul_i32 s5, s5, 0xc000
	s_add_u32 s6, s11, s5
	s_addc_u32 s7, s12, s7
	s_waitcnt lgkmcnt(0)
	v_add_f32_e32 v64, v64, v65
	ds_bpermute_b32 v65, v88, v64
	s_add_u32 s8, s6, 0x2000
	s_addc_u32 s9, s7, 0
	v_lshl_add_u64 v[86:87], s[8:9], 0, v[178:179]
	v_mov_b32_e32 v79, v179
	s_waitcnt lgkmcnt(0)
	v_add_f32_e32 v64, v64, v65
	ds_bpermute_b32 v65, v89, v64
	v_mov_b32_e32 v81, v179
	v_mov_b32_e32 v83, v179
	s_add_i32 s10, s10, -1
	s_cmp_lg_u32 s10, 0
	s_waitcnt lgkmcnt(0)
	v_add_f32_e32 v64, v64, v65
	ds_bpermute_b32 v65, v90, v64
	s_waitcnt lgkmcnt(0)
	v_add_f32_e32 v64, v64, v65
	ds_bpermute_b32 v65, v91, v64
	s_waitcnt lgkmcnt(0)
	v_add_f32_e32 v64, v64, v65
	v_fmamk_f32 v64, v64, 0x3a000000, v200
	v_cmp_gt_f32_e32 vcc, s96, v64
	v_mul_f32_e32 v65, 0x4b800000, v64
	s_nop 0
	v_cndmask_b32_e32 v64, v64, v65, vcc
	v_rsq_f32_e32 v64, v64
	s_nop 0
	v_mul_f32_e32 v65, 0x45800000, v64
	v_cndmask_b32_e32 v84, v64, v65, vcc
	global_load_dwordx4 v[64:67], v[70:71], off offset:16
	global_load_dwordx4 v[92:95], v[70:71], off
	flat_load_dwordx4 v[96:99], v[86:87]
	flat_load_dwordx4 v[100:103], v[86:87] offset:16
	v_lshl_add_u64 v[86:87], s[6:7], 0, v[178:179]
	flat_load_dwordx4 v[104:107], v[86:87]
	flat_load_dwordx4 v[108:111], v[86:87] offset:16
	v_pk_mul_f32 v[58:59], v[58:59], v[84:85] op_sel_hi:[1,0]
	v_pk_mul_f32 v[56:57], v[56:57], v[84:85] op_sel_hi:[1,0]
	v_pk_mul_f32 v[62:63], v[62:63], v[84:85] op_sel_hi:[1,0]
	v_pk_mul_f32 v[60:61], v[60:61], v[84:85] op_sel_hi:[1,0]
	v_pk_mul_f32 v[50:51], v[50:51], v[84:85] op_sel_hi:[1,0]
	v_pk_mul_f32 v[48:49], v[48:49], v[84:85] op_sel_hi:[1,0]
	v_pk_mul_f32 v[54:55], v[54:55], v[84:85] op_sel_hi:[1,0]
	v_pk_mul_f32 v[52:53], v[52:53], v[84:85] op_sel_hi:[1,0]
	v_pk_mul_f32 v[42:43], v[42:43], v[84:85] op_sel_hi:[1,0]
	v_pk_mul_f32 v[40:41], v[40:41], v[84:85] op_sel_hi:[1,0]
	v_pk_mul_f32 v[46:47], v[46:47], v[84:85] op_sel_hi:[1,0]
	v_pk_mul_f32 v[44:45], v[44:45], v[84:85] op_sel_hi:[1,0]
	v_pk_mul_f32 v[6:7], v[6:7], v[84:85] op_sel_hi:[1,0]
	v_pk_mul_f32 v[4:5], v[4:5], v[84:85] op_sel_hi:[1,0]
	v_pk_mul_f32 v[10:11], v[10:11], v[84:85] op_sel_hi:[1,0]
	v_pk_mul_f32 v[8:9], v[8:9], v[84:85] op_sel_hi:[1,0]
	s_waitcnt vmcnt(0)
	v_pk_mul_f32 v[56:57], v[64:65], v[56:57]
	v_pk_mul_f32 v[58:59], v[66:67], v[58:59]
	s_waitcnt lgkmcnt(0)
	v_pk_add_f32 v[64:65], v[102:103], 1.0 op_sel_hi:[1,0]
	v_pk_add_f32 v[66:67], v[100:101], 1.0 op_sel_hi:[1,0]
	v_pk_mul_f32 v[60:61], v[92:93], v[60:61]
	v_pk_mul_f32 v[62:63], v[94:95], v[62:63]
	v_pk_add_f32 v[92:93], v[98:99], 1.0 op_sel_hi:[1,0]
	v_pk_add_f32 v[94:95], v[96:97], 1.0 op_sel_hi:[1,0]
	v_pk_fma_f32 v[64:65], v[64:65], v[58:59], v[110:111]
	v_pk_fma_f32 v[58:59], v[66:67], v[56:57], v[108:109]
	v_pk_fma_f32 v[62:63], v[92:93], v[62:63], v[106:107]
	v_pk_fma_f32 v[60:61], v[94:95], v[60:61], v[104:105]
	v_lshl_add_u64 v[92:93], s[8:9], 0, v[78:79]
	v_cvt_pk_bf16_f32 v56, v60, v61
	v_cvt_pk_bf16_f32 v57, v62, v63
	v_cvt_pk_bf16_f32 v58, v58, v59
	v_cvt_pk_bf16_f32 v59, v64, v65
	flat_store_dwordx4 v[76:77], v[56:59]
	global_load_dwordx4 v[56:59], v[70:71], off offset:2064
	s_nop 0
	global_load_dwordx4 v[60:63], v[70:71], off offset:2048
	flat_load_dwordx4 v[64:67], v[92:93]
	s_nop 0
	flat_load_dwordx4 v[92:95], v[92:93] offset:16
	s_nop 0
	flat_load_dwordx4 v[96:99], v[86:87] offset:2048
	flat_load_dwordx4 v[100:103], v[86:87] offset:2064
	v_lshl_add_u64 v[86:87], s[6:7], 0, v[80:81]
	s_waitcnt vmcnt(0)
	v_pk_mul_f32 v[52:53], v[52:53], v[56:57]
	v_pk_mul_f32 v[48:49], v[48:49], v[60:61]
	v_pk_mul_f32 v[50:51], v[50:51], v[62:63]
	s_waitcnt lgkmcnt(0)
	v_pk_add_f32 v[60:61], v[66:67], 1.0 op_sel_hi:[1,0]
	v_pk_add_f32 v[62:63], v[64:65], 1.0 op_sel_hi:[1,0]
	v_pk_fma_f32 v[50:51], v[50:51], v[60:61], v[98:99]
	v_pk_fma_f32 v[48:49], v[48:49], v[62:63], v[96:97]
	v_pk_mul_f32 v[54:55], v[54:55], v[58:59]
	v_pk_add_f32 v[56:57], v[94:95], 1.0 op_sel_hi:[1,0]
	v_pk_add_f32 v[58:59], v[92:93], 1.0 op_sel_hi:[1,0]
	v_pk_fma_f32 v[54:55], v[54:55], v[56:57], v[102:103]
	v_pk_fma_f32 v[52:53], v[52:53], v[58:59], v[100:101]
	v_cvt_pk_bf16_f32 v48, v48, v49
	v_cvt_pk_bf16_f32 v49, v50, v51
	v_lshl_add_u64 v[60:61], s[8:9], 0, v[80:81]
	v_cvt_pk_bf16_f32 v50, v52, v53
	v_cvt_pk_bf16_f32 v51, v54, v55
	flat_store_dwordx4 v[76:77], v[48:51] offset:1024
	global_load_dwordx4 v[48:51], v[72:73], off offset:16
	s_nop 0
	global_load_dwordx4 v[52:55], v[72:73], off
	flat_load_dwordx4 v[56:59], v[60:61]
	s_nop 0
	flat_load_dwordx4 v[60:63], v[60:61] offset:16
	s_nop 0
	flat_load_dwordx4 v[64:67], v[86:87]
	flat_load_dwordx4 v[92:95], v[86:87] offset:16
	s_waitcnt vmcnt(0)
	v_pk_mul_f32 v[44:45], v[44:45], v[48:49]
	v_pk_mul_f32 v[40:41], v[40:41], v[52:53]
	v_pk_mul_f32 v[42:43], v[42:43], v[54:55]
	s_waitcnt lgkmcnt(0)
	v_pk_add_f32 v[52:53], v[58:59], 1.0 op_sel_hi:[1,0]
	v_pk_add_f32 v[54:55], v[56:57], 1.0 op_sel_hi:[1,0]
	v_pk_fma_f32 v[42:43], v[42:43], v[52:53], v[66:67]
	v_pk_fma_f32 v[40:41], v[40:41], v[54:55], v[64:65]
	v_pk_mul_f32 v[46:47], v[46:47], v[50:51]
	v_pk_add_f32 v[48:49], v[62:63], 1.0 op_sel_hi:[1,0]
	v_pk_add_f32 v[50:51], v[60:61], 1.0 op_sel_hi:[1,0]
	v_pk_fma_f32 v[46:47], v[46:47], v[48:49], v[94:95]
	v_pk_fma_f32 v[44:45], v[44:45], v[50:51], v[92:93]
	v_cvt_pk_bf16_f32 v40, v40, v41
	v_cvt_pk_bf16_f32 v41, v42, v43
	v_lshl_add_u64 v[52:53], s[8:9], 0, v[82:83]
	v_cvt_pk_bf16_f32 v42, v44, v45
	v_cvt_pk_bf16_f32 v43, v46, v47
	flat_store_dwordx4 v[76:77], v[40:43] offset:2048
	global_load_dwordx4 v[40:43], v[74:75], off offset:16
	s_nop 0
	global_load_dwordx4 v[44:47], v[74:75], off
	flat_load_dwordx4 v[48:51], v[52:53]
	s_nop 0
	flat_load_dwordx4 v[52:55], v[52:53] offset:16
	v_lshl_add_u64 v[60:61], s[6:7], 0, v[82:83]
	flat_load_dwordx4 v[56:59], v[60:61]
	s_nop 0
	flat_load_dwordx4 v[60:63], v[60:61] offset:16
	v_readlane_b32 s6, v254, 38
	v_readlane_b32 s7, v254, 39
	s_waitcnt vmcnt(0)
	v_pk_mul_f32 v[8:9], v[8:9], v[40:41]
	v_pk_mul_f32 v[4:5], v[4:5], v[44:45]
	v_pk_mul_f32 v[6:7], v[6:7], v[46:47]
	s_waitcnt lgkmcnt(0)
	v_pk_add_f32 v[44:45], v[50:51], 1.0 op_sel_hi:[1,0]
	v_pk_add_f32 v[46:47], v[48:49], 1.0 op_sel_hi:[1,0]
	v_pk_fma_f32 v[6:7], v[6:7], v[44:45], v[58:59]
	v_pk_fma_f32 v[4:5], v[4:5], v[46:47], v[56:57]
	v_pk_mul_f32 v[10:11], v[10:11], v[42:43]
	v_pk_add_f32 v[40:41], v[54:55], 1.0 op_sel_hi:[1,0]
	v_pk_add_f32 v[42:43], v[52:53], 1.0 op_sel_hi:[1,0]
	v_pk_fma_f32 v[10:11], v[10:11], v[40:41], v[62:63]
	v_pk_fma_f32 v[8:9], v[8:9], v[42:43], v[60:61]
	v_cvt_pk_bf16_f32 v4, v4, v5
	v_cvt_pk_bf16_f32 v5, v6, v7
	v_mov_b32_e32 v60, v36
	v_cvt_pk_bf16_f32 v6, v8, v9
	v_cvt_pk_bf16_f32 v7, v10, v11
	flat_store_dwordx4 v[76:77], v[4:7] offset:3072
	v_lshl_add_u64 v[76:77], v[76:77], 0, s[6:7]
	s_mov_b32 s6, s4
	v_mov_b32_e32 v61, v37
	v_mov_b32_e32 v62, v38
	v_mov_b32_e32 v63, v39
	v_mov_b32_e32 v56, v24
	v_mov_b32_e32 v57, v25
	v_mov_b32_e32 v58, v26
	v_mov_b32_e32 v59, v27
	v_mov_b32_e32 v48, v32
	v_mov_b32_e32 v49, v33
	v_mov_b32_e32 v50, v34
	v_mov_b32_e32 v51, v35
	v_mov_b32_e32 v52, v16
	v_mov_b32_e32 v53, v17
	v_mov_b32_e32 v54, v18
	v_mov_b32_e32 v55, v19
	v_mov_b32_e32 v40, v28
	v_mov_b32_e32 v41, v29
	v_mov_b32_e32 v42, v30
	v_mov_b32_e32 v43, v31
	v_mov_b32_e32 v44, v12
	v_mov_b32_e32 v45, v13
	v_mov_b32_e32 v46, v14
	v_mov_b32_e32 v47, v15
	v_mov_b32_e32 v4, v20
	v_mov_b32_e32 v5, v21
	v_mov_b32_e32 v6, v22
	v_mov_b32_e32 v7, v23
	v_mov_b32_e32 v8, v0
	v_mov_b32_e32 v9, v1
	v_mov_b32_e32 v10, v2
	v_mov_b32_e32 v11, v3
	s_cbranch_scc0 .LBB0_1144
